# prompt attention loop: forget-bias inputs for the next tile no longer waited (vmcnt(0)) at the loop top by wave 0; computed at the loop bottom
# speedup vs baseline: 1.0092x; 1.0008x over previous
; __device__ __forceinline__ void attn_unit(const Args& a, LAS unsigned char* lds, const int mode, const int h, const int qb, const int tid_in, const int lane_in, const int wave) {
;     ...
;             const int krow = mode == 0 ? j * 64 : MP + qb * 64;
;             const size_t off = (size_t)(krow + sr) * D + h * HD + sc8 * 8;
;             kst[0] = *(const f32x4*)(Kb + off); vst[0] = *(const f32x4*)(Vb + off);
;             if (tid < 64) { const float pfx = mode == 0 ? ((const float*)(ws + WS_PFXP))[h * 256 + j] : ((const float*)(ws + WS_PFXS))[qb * 16 + h];
;                 ckst = (pfx + CLT[krow + tid]) * L2E; }
.LBB0_522:
	s_add_i32 s0, s12, s17
	s_add_i32 s0, s0, 1
	s_cmp_lt_i32 s0, s16
	s_cselect_b64 s[4:5], -1, 0
	s_cmp_ge_i32 s0, s16
	s_cbranch_scc1 .LBB0_526
	v_add_u32_e32 v34, s13, v107
	v_ashrrev_i32_e32 v35, 31, v34
	v_lshlrev_b64 v[34:35], 11, v[34:35]
	v_lshl_or_b32 v34, v94, 1, v34
	v_lshl_add_u64 v[36:37], s[38:39], 0, v[34:35]
	v_lshl_add_u64 v[34:35], s[40:41], 0, v[34:35]
	global_load_dwordx4 v[82:85], v[36:37], off
	global_load_dwordx4 v[86:89], v[34:35], off
	s_and_saveexec_b64 s[0:1], s[2:3]
	s_cbranch_execz .LBB0_525
	s_add_i32 s6, s15, s17
	s_ashr_i32 s7, s6, 31
	v_add_u32_e32 v34, s13, v106
	s_lshl_b64 s[6:7], s[6:7], 2
	v_ashrrev_i32_e32 v35, 31, v34
	s_add_u32 s6, s60, s6
	v_lshl_add_u64 v[34:35], v[34:35], 2, s[8:9]
	s_addc_u32 s7, s61, s7
	global_load_dword v194, v0, s[6:7]
	s_nop 0
	global_load_dword v195, v[34:35], off

; #define LAS __attribute__((address_space(3)))
; __device__ __forceinline__ void attn_unit(const Args& a, LAS unsigned char* lds, const int mode, const int h, const int qb, const int tid_in, const int lane_in, const int wave) {
;     ...
;         *(LAS u32x4*)(lds + AT_K + buf * AT_KB + sr * 144 + sc8 * 16) = kw;
;         *(LAS u32x4*)(lds + AT_V + buf * AT_VB + sr * 160 + sc8 * 16) = vw;
;         if (tid < 64) *(LAS float*)(lds + AT_CK + buf * 256 + tid * 4) = ckst;
.LBB0_536:
	s_or_b64 exec, exec, s[6:7]
	s_andn2_b64 vcc, exec, s[4:5]
	s_cbranch_vccnz .LBB0_521
	s_xor_b32 s4, s18, 1
	s_mul_i32 s0, s4, 0x2400
	v_add_u32_e32 v34, s0, v91
	s_mul_i32 s0, s4, 0x2800
	s_waitcnt vmcnt(1)
	ds_write_b128 v34, v[82:85]
	v_add_u32_e32 v34, s0, v95
	s_waitcnt vmcnt(0)
	ds_write_b128 v34, v[86:89] offset:18432
	s_and_saveexec_b64 s[0:1], s[2:3]
	s_cbranch_execz .LBB0_520
	v_lshl_add_u32 v34, s4, 8, v96
	v_add_f32_e32 v97, v194, v195
	v_mul_f32_e32 v97, 0x3fb8aa3b, v97
	ds_write_b32 v34, v97 offset:38912
	s_branch .LBB0_520
